# XCD-local barriers now a single per-XCC arrival counter that every workgroup polls (no leader / release word); rest as v37
# speedup vs baseline: 1.0071x; 1.0033x over previous
.LBB0_2079:
	s_mov_b32 s4, s71
	s_waitcnt vmcnt(0)
	s_waitcnt lgkmcnt(0)
	s_barrier
	s_and_saveexec_b64 s[6:7], s[26:27]
	s_cbranch_execz .LBB0_2116
	v_readlane_b32 s0, v255, 17
	s_waitcnt vmcnt(0) expcnt(0) lgkmcnt(0)
	s_mov_b64 s[16:17], exec
	v_mov_b32_e32 v0, s0
	v_readlane_b32 s0, v255, 18
	ds_read_b32 v2, v0
	v_mbcnt_lo_u32_b32 v1, s16, 0
	v_mov_b32_e32 v0, s0
	ds_read_b32 v0, v0
	v_mbcnt_hi_u32_b32 v1, s17, v1
	s_lshl_b32 s4, s4, 6
	v_cmp_eq_u32_e32 vcc, 0, v1
	s_and_saveexec_b64 s[18:19], vcc
	s_cbranch_execz .LBB0_2082
	v_readlane_b32 s0, v255, 46
	s_lshr_b32 s1, s4, 1
	s_add_i32 s1, s1, 0xe50
	s_add_i32 s96, s4, 0x500
	s_cmp_lg_u32 s0, 0
	s_cselect_b32 s96, s1, s96
	s_lshl_b64 s[0:1], s[96:97], 2
	v_readlane_b32 s8, v254, 10
	v_readlane_b32 s9, v254, 11
	s_add_u32 s0, s8, s0
	s_addc_u32 s1, s9, s1
	s_bcnt1_i32_b64 s5, s[16:17]
	v_mov_b32_e32 v3, s5
	global_atomic_add v3, v65, v3, s[0:1] sc0
.LBB0_2082:
	s_or_b64 exec, exec, s[18:19]
	s_waitcnt lgkmcnt(1)
	v_cvt_f32_u32_e32 v4, v2
	s_waitcnt vmcnt(0)
	v_readfirstlane_b32 s0, v3
	buffer_inv sc1
	v_sub_u32_e32 v3, 0, v2
	v_rcp_iflag_f32_e32 v4, v4
	v_add_u32_e32 v5, s0, v1
	v_mul_f32_e32 v4, 0x4f7ffffe, v4
	v_cvt_u32_f32_e32 v4, v4
	v_mul_lo_u32 v1, v3, v4
	v_mul_hi_u32 v1, v4, v1
	v_add_u32_e32 v1, v4, v1
	v_mul_hi_u32 v1, v5, v1
	v_mul_lo_u32 v3, v1, v2
	v_sub_u32_e32 v3, v5, v3
	v_add_u32_e32 v4, 1, v1
	v_cmp_ge_u32_e32 vcc, v3, v2
	s_nop 1
	v_cndmask_b32_e32 v1, v1, v4, vcc
	v_sub_u32_e32 v4, v3, v2
	v_cndmask_b32_e32 v3, v3, v4, vcc
	v_add_u32_e32 v4, 1, v1
	v_cmp_ge_u32_e32 vcc, v3, v2
	v_add_u32_e32 v3, 1, v5
	s_nop 0
	v_cndmask_b32_e32 v1, v1, v4, vcc
	v_mul_lo_u32 v4, v2, v1
	v_add_u32_e32 v2, v4, v2
	v_cmp_ne_u32_e32 vcc, v3, v2
	s_and_saveexec_b64 s[0:1], vcc
	s_xor_b64 s[16:17], exec, s[0:1]
	s_cbranch_execz .LBB0_2096
	v_readlane_b32 s0, v255, 46
	s_cmp_lg_u32 s0, 0
	s_cbranch_scc0 .Lmy_gpoll_a
	s_lshr_b32 s96, s4, 1
	s_add_i32 s96, s96, 0xe50
	s_lshl_b64 s[0:1], s[96:97], 2
	v_readlane_b32 s8, v254, 10
	v_readlane_b32 s9, v254, 11
	s_add_u32 s20, s8, s0
	s_addc_u32 s21, s9, s1
	s_mov_b32 s5, 0
	s_waitcnt lgkmcnt(0)
.Lmy_lpoll_a:
	global_load_dword v0, v65, s[20:21] sc1
	s_waitcnt vmcnt(0)
	v_cmp_lt_u32_e32 vcc, v0, v2
	s_cbranch_vccz .LBB0_2096
	s_sleep 1
	s_add_i32 s5, s5, 1
	s_cmp_lt_u32 s5, 0x100000
	s_cbranch_scc1 .Lmy_lpoll_a
	s_branch .LBB0_2096
.Lmy_gpoll_a:
	s_add_i32 s96, s4, 0x900
	s_lshl_b64 s[0:1], s[96:97], 2
	v_readlane_b32 s8, v254, 10
	v_readlane_b32 s9, v254, 11
	s_add_u32 s20, s8, s0
	s_addc_u32 s21, s9, s1
	s_waitcnt lgkmcnt(0)
	global_load_dword v0, v65, s[20:21] sc1
	s_waitcnt vmcnt(0)
	v_cmp_eq_u32_e32 vcc, v0, v1
	s_and_saveexec_b64 s[18:19], vcc
	s_cbranch_execz .LBB0_2095
	s_mov_b32 s5, 1
	s_mov_b64 s[22:23], 0
	s_branch .LBB0_2086

.LBB0_2096:
	s_andn2_saveexec_b64 s[0:1], s[16:17]
	s_cbranch_execz .LBB0_2116
	v_readlane_b32 s0, v255, 46
	s_cmp_lg_u32 s0, 0
	s_cbranch_scc0 .Lmy_gl_a
	s_waitcnt vmcnt(0)
	s_branch .LBB0_2116
.Lmy_gl_a:
	s_mov_b64 s[16:17], exec
	buffer_wbl2 sc1
	s_waitcnt lgkmcnt(0)
	s_waitcnt vmcnt(0)
	v_mbcnt_lo_u32_b32 v1, s16, 0
	v_mbcnt_hi_u32_b32 v1, s17, v1
	v_cmp_eq_u32_e32 vcc, 0, v1
	s_and_saveexec_b64 s[18:19], vcc
	s_cbranch_execz .LBB0_2099
	s_bcnt1_i32_b64 s0, s[16:17]
	v_mov_b32_e32 v2, s0
	v_readlane_b32 s0, v254, 25
	v_readlane_b32 s1, v254, 26
	s_nop 4
	global_atomic_add v2, v65, v2, s[0:1] sc0

.LBB0_2132:
	s_mov_b32 s4, s71
	s_waitcnt vmcnt(0)
	s_waitcnt lgkmcnt(0)
	s_barrier
	s_and_saveexec_b64 s[6:7], s[26:27]
	v_readlane_b32 s33, v255, 29
	s_cbranch_execz .LBB0_2169
	v_readlane_b32 s0, v255, 17
	s_waitcnt vmcnt(0) expcnt(0) lgkmcnt(0)
	s_mov_b64 s[18:19], exec
	v_mov_b32_e32 v0, s0
	v_readlane_b32 s0, v255, 18
	ds_read_b32 v2, v0
	v_mbcnt_lo_u32_b32 v1, s18, 0
	v_mov_b32_e32 v0, s0
	ds_read_b32 v0, v0
	v_mbcnt_hi_u32_b32 v1, s19, v1
	s_lshl_b32 s4, s4, 6
	v_cmp_eq_u32_e32 vcc, 0, v1
	s_and_saveexec_b64 s[20:21], vcc
	s_cbranch_execz .LBB0_2135
	v_readlane_b32 s0, v255, 46
	s_lshr_b32 s1, s4, 1
	s_add_i32 s1, s1, 0xe50
	s_add_i32 s96, s4, 0x500
	s_cmp_lg_u32 s0, 0
	s_cselect_b32 s96, s1, s96
	s_lshl_b64 s[0:1], s[96:97], 2
	v_readlane_b32 s8, v254, 10
	v_readlane_b32 s9, v254, 11
	s_add_u32 s0, s8, s0
	s_addc_u32 s1, s9, s1
	s_bcnt1_i32_b64 s5, s[18:19]
	v_mov_b32_e32 v3, s5
	global_atomic_add v3, v65, v3, s[0:1] sc0
.LBB0_2135:
	s_or_b64 exec, exec, s[20:21]
	s_waitcnt lgkmcnt(1)
	v_cvt_f32_u32_e32 v4, v2
	s_waitcnt vmcnt(0)
	v_readfirstlane_b32 s0, v3
	buffer_inv sc1
	v_sub_u32_e32 v3, 0, v2
	v_rcp_iflag_f32_e32 v4, v4
	v_add_u32_e32 v5, s0, v1
	v_mul_f32_e32 v4, 0x4f7ffffe, v4
	v_cvt_u32_f32_e32 v4, v4
	v_mul_lo_u32 v1, v3, v4
	v_mul_hi_u32 v1, v4, v1
	v_add_u32_e32 v1, v4, v1
	v_mul_hi_u32 v1, v5, v1
	v_mul_lo_u32 v3, v1, v2
	v_sub_u32_e32 v3, v5, v3
	v_add_u32_e32 v4, 1, v1
	v_cmp_ge_u32_e32 vcc, v3, v2
	s_nop 1
	v_cndmask_b32_e32 v1, v1, v4, vcc
	v_sub_u32_e32 v4, v3, v2
	v_cndmask_b32_e32 v3, v3, v4, vcc
	v_add_u32_e32 v4, 1, v1
	v_cmp_ge_u32_e32 vcc, v3, v2
	v_add_u32_e32 v3, 1, v5
	s_nop 0
	v_cndmask_b32_e32 v1, v1, v4, vcc
	v_mul_lo_u32 v4, v2, v1
	v_add_u32_e32 v2, v4, v2
	v_cmp_ne_u32_e32 vcc, v3, v2
	s_and_saveexec_b64 s[0:1], vcc
	s_xor_b64 s[18:19], exec, s[0:1]
	s_cbranch_execz .LBB0_2149
	v_readlane_b32 s0, v255, 46
	s_cmp_lg_u32 s0, 0
	s_cbranch_scc0 .Lmy_gpoll_b
	s_lshr_b32 s96, s4, 1
	s_add_i32 s96, s96, 0xe50
	s_lshl_b64 s[0:1], s[96:97], 2
	v_readlane_b32 s8, v254, 10
	v_readlane_b32 s9, v254, 11
	s_add_u32 s22, s8, s0
	s_addc_u32 s23, s9, s1
	s_mov_b32 s5, 0
	s_waitcnt lgkmcnt(0)
.Lmy_lpoll_b:
	global_load_dword v0, v65, s[22:23] sc1
	s_waitcnt vmcnt(0)
	v_cmp_lt_u32_e32 vcc, v0, v2
	s_cbranch_vccz .LBB0_2149
	s_sleep 1
	s_add_i32 s5, s5, 1
	s_cmp_lt_u32 s5, 0x100000
	s_cbranch_scc1 .Lmy_lpoll_b
	s_branch .LBB0_2149
.Lmy_gpoll_b:
	s_add_i32 s96, s4, 0x900
	s_lshl_b64 s[0:1], s[96:97], 2
	v_readlane_b32 s8, v254, 10
	v_readlane_b32 s9, v254, 11
	s_add_u32 s22, s8, s0
	s_addc_u32 s23, s9, s1
	s_waitcnt lgkmcnt(0)
	global_load_dword v0, v65, s[22:23] sc1
	s_waitcnt vmcnt(0)
	v_cmp_eq_u32_e32 vcc, v0, v1
	s_and_saveexec_b64 s[20:21], vcc
	s_cbranch_execz .LBB0_2148
	s_mov_b32 s5, 1
	s_mov_b64 s[24:25], 0
	s_branch .LBB0_2139

.LBB0_2149:
	s_andn2_saveexec_b64 s[0:1], s[18:19]
	s_cbranch_execz .LBB0_2169
	v_readlane_b32 s0, v255, 46
	s_cmp_lg_u32 s0, 0
	s_cbranch_scc0 .Lmy_gl_b
	s_waitcnt vmcnt(0)
	s_branch .LBB0_2169
.Lmy_gl_b:
	s_mov_b64 s[18:19], exec
	buffer_wbl2 sc1
	s_waitcnt lgkmcnt(0)
	s_waitcnt vmcnt(0)
	v_mbcnt_lo_u32_b32 v1, s18, 0
	v_mbcnt_hi_u32_b32 v1, s19, v1
	v_cmp_eq_u32_e32 vcc, 0, v1
	s_and_saveexec_b64 s[20:21], vcc
	s_cbranch_execz .LBB0_2152
	s_bcnt1_i32_b64 s0, s[18:19]
	v_mov_b32_e32 v2, s0
	v_readlane_b32 s0, v254, 25
	v_readlane_b32 s1, v254, 26
	s_nop 4
	global_atomic_add v2, v65, v2, s[0:1] sc0
